# plus hand-written chunk-state scan: decay slice via LDS, 24 state loads in flight, counted waits
# speedup vs baseline: 1.0061x; 1.0061x over previous
; __device__ __forceinline__ unsigned f2bf(float f) { return pk2(f, 0.f) & 0xffffu; }
; __device__ __forceinline__ void hgrn_scan(const float* US, const float* DD, bf16* SB, int gtid, int gstride) {
;     for (int e = gtid; e < 8 * 16384; e += gstride) { const int chain = e >> 14, idx = e & 16383, k = idx & 127; float run = 0.f;
;         for (int c0 = 0; c0 < 64; c0 += 16) { float u[16], d[16];
; #pragma unroll
;             for (int j = 0; j < 16; ++j) { u[j] = US[(size_t)(chain * 64 + c0 + j) * 16384 + idx]; d[j] = DD[(chain * 64 + c0 + j) * 128 + k]; }
; #pragma unroll
;             for (int j = 0; j < 16; ++j) { SB[(size_t)(chain * 64 + c0 + j) * 16384 + idx] = (bf16)f2bf(run); run = d[j] * run + u[j]; } } }
; }
.LBB0_641:
	s_or_b64 exec, exec, s[0:1]
	s_waitcnt lgkmcnt(1)
	v_mov_b32_e32 v0, v252
	v_readlane_b32 s0, v254, 38
	s_waitcnt lgkmcnt(0)
	s_barrier
	s_cmpk_lg_i32 s86, 0x100
	s_cbranch_scc1 .Lscan_orig
	s_lshr_b32 s14, s0, 14
	v_add_u32_e32 v1, s0, v0
	v_and_b32_e32 v1, 0x3fff, v1
	v_lshlrev_b32_e32 v2, 1, v1
	v_lshlrev_b32_e32 v1, 2, v1
	v_and_b32_e32 v3, 0x7f, v0
	v_lshlrev_b32_e32 v3, 2, v3
	v_lshlrev_b32_e32 v4, 4, v0
	v_mov_b32_e32 v6, 0
	s_lshl_b32 s15, s14, 15
	s_add_u32 s2, s20, 0x1d800000
	s_addc_u32 s3, s21, 0
	s_add_u32 s2, s2, s15
	s_addc_u32 s3, s3, 0
	s_lshl_b32 s15, s14, 22
	s_add_u32 s4, s20, 0x1a800000
	s_addc_u32 s5, s21, 0
	s_add_u32 s4, s4, s15
	s_addc_u32 s5, s5, 0
	s_lshl_b32 s15, s14, 21
	s_add_u32 s8, s20, 0x1c800000
	s_addc_u32 s9, s21, 0
	s_add_u32 s8, s8, s15
	s_addc_u32 s9, s9, 0
	global_load_dwordx4 v[8:11], v4, s[2:3]
	v_add_u32_e32 v5, 0x2000, v4
	global_load_dwordx4 v[12:15], v5, s[2:3]
	v_add_u32_e32 v5, 0x4000, v4
	global_load_dwordx4 v[16:19], v5, s[2:3]
	v_add_u32_e32 v5, 0x6000, v4
	global_load_dwordx4 v[20:23], v5, s[2:3]
	global_load_dword v32, v1, s[4:5]
	s_add_u32 s4, s4, 0x10000
	s_addc_u32 s5, s5, 0
	global_load_dword v33, v1, s[4:5]
	s_add_u32 s4, s4, 0x10000
	s_addc_u32 s5, s5, 0
	global_load_dword v34, v1, s[4:5]
	s_add_u32 s4, s4, 0x10000
	s_addc_u32 s5, s5, 0
	global_load_dword v35, v1, s[4:5]
	s_add_u32 s4, s4, 0x10000
	s_addc_u32 s5, s5, 0
	global_load_dword v36, v1, s[4:5]
	s_add_u32 s4, s4, 0x10000
	s_addc_u32 s5, s5, 0
	global_load_dword v37, v1, s[4:5]
	s_add_u32 s4, s4, 0x10000
	s_addc_u32 s5, s5, 0
	global_load_dword v38, v1, s[4:5]
	s_add_u32 s4, s4, 0x10000
	s_addc_u32 s5, s5, 0
	global_load_dword v39, v1, s[4:5]
	s_add_u32 s4, s4, 0x10000
	s_addc_u32 s5, s5, 0
	global_load_dword v40, v1, s[4:5]
	s_add_u32 s4, s4, 0x10000
	s_addc_u32 s5, s5, 0
	global_load_dword v41, v1, s[4:5]
	s_add_u32 s4, s4, 0x10000
	s_addc_u32 s5, s5, 0
	global_load_dword v42, v1, s[4:5]
	s_add_u32 s4, s4, 0x10000
	s_addc_u32 s5, s5, 0
	global_load_dword v43, v1, s[4:5]
	s_add_u32 s4, s4, 0x10000
	s_addc_u32 s5, s5, 0
	global_load_dword v44, v1, s[4:5]
	s_add_u32 s4, s4, 0x10000
	s_addc_u32 s5, s5, 0
	global_load_dword v45, v1, s[4:5]
	s_add_u32 s4, s4, 0x10000
	s_addc_u32 s5, s5, 0
	global_load_dword v46, v1, s[4:5]
	s_add_u32 s4, s4, 0x10000
	s_addc_u32 s5, s5, 0
	global_load_dword v47, v1, s[4:5]
	s_add_u32 s4, s4, 0x10000
	s_addc_u32 s5, s5, 0
	global_load_dword v48, v1, s[4:5]
	s_add_u32 s4, s4, 0x10000
	s_addc_u32 s5, s5, 0
	global_load_dword v49, v1, s[4:5]
	s_add_u32 s4, s4, 0x10000
	s_addc_u32 s5, s5, 0
	global_load_dword v50, v1, s[4:5]
	s_add_u32 s4, s4, 0x10000
	s_addc_u32 s5, s5, 0
	global_load_dword v51, v1, s[4:5]
	s_add_u32 s4, s4, 0x10000
	s_addc_u32 s5, s5, 0
	global_load_dword v52, v1, s[4:5]
	s_add_u32 s4, s4, 0x10000
	s_addc_u32 s5, s5, 0
	global_load_dword v53, v1, s[4:5]
	s_add_u32 s4, s4, 0x10000
	s_addc_u32 s5, s5, 0
	global_load_dword v54, v1, s[4:5]
	s_add_u32 s4, s4, 0x10000
	s_addc_u32 s5, s5, 0
	global_load_dword v55, v1, s[4:5]
	s_add_u32 s4, s4, 0x10000
	s_addc_u32 s5, s5, 0
	s_waitcnt vmcnt(24)
	ds_write_b128 v4, v[8:11]
	ds_write_b128 v4, v[12:15] offset:8192
	ds_write_b128 v4, v[16:19] offset:16384
	ds_write_b128 v4, v[20:23] offset:24576
	s_waitcnt lgkmcnt(0)
	s_barrier
	ds_read_b32 v96, v3
	ds_read_b32 v97, v3 offset:512
	ds_read_b32 v98, v3 offset:1024
	ds_read_b32 v99, v3 offset:1536
	ds_read_b32 v100, v3 offset:2048
	ds_read_b32 v101, v3 offset:2560
	ds_read_b32 v102, v3 offset:3072
	ds_read_b32 v103, v3 offset:3584
	s_waitcnt lgkmcnt(0)
	ds_read_b32 v104, v3 offset:4096
	ds_read_b32 v105, v3 offset:4608
	ds_read_b32 v106, v3 offset:5120
	ds_read_b32 v107, v3 offset:5632
	ds_read_b32 v108, v3 offset:6144
	ds_read_b32 v109, v3 offset:6656
	ds_read_b32 v110, v3 offset:7168
	ds_read_b32 v111, v3 offset:7680
	s_waitcnt lgkmcnt(0)
	ds_read_b32 v112, v3 offset:8192
	ds_read_b32 v113, v3 offset:8704
	ds_read_b32 v114, v3 offset:9216
	ds_read_b32 v115, v3 offset:9728
	ds_read_b32 v116, v3 offset:10240
	ds_read_b32 v117, v3 offset:10752
	ds_read_b32 v118, v3 offset:11264
	ds_read_b32 v119, v3 offset:11776
	s_waitcnt lgkmcnt(0)
	ds_read_b32 v120, v3 offset:12288
	ds_read_b32 v121, v3 offset:12800
	ds_read_b32 v122, v3 offset:13312
	ds_read_b32 v123, v3 offset:13824
	ds_read_b32 v124, v3 offset:14336
	ds_read_b32 v125, v3 offset:14848
	ds_read_b32 v126, v3 offset:15360
	ds_read_b32 v127, v3 offset:15872
	s_waitcnt lgkmcnt(0)
	ds_read_b32 v128, v3 offset:16384
	ds_read_b32 v129, v3 offset:16896
	ds_read_b32 v130, v3 offset:17408
	ds_read_b32 v131, v3 offset:17920
	ds_read_b32 v132, v3 offset:18432
	ds_read_b32 v133, v3 offset:18944
	ds_read_b32 v134, v3 offset:19456
	ds_read_b32 v135, v3 offset:19968
	s_waitcnt lgkmcnt(0)
	ds_read_b32 v136, v3 offset:20480
	ds_read_b32 v137, v3 offset:20992
	ds_read_b32 v138, v3 offset:21504
	ds_read_b32 v139, v3 offset:22016
	ds_read_b32 v140, v3 offset:22528
	ds_read_b32 v141, v3 offset:23040
	ds_read_b32 v142, v3 offset:23552
	ds_read_b32 v143, v3 offset:24064
	s_waitcnt lgkmcnt(0)
	ds_read_b32 v144, v3 offset:24576
	ds_read_b32 v145, v3 offset:25088
	ds_read_b32 v146, v3 offset:25600
	ds_read_b32 v147, v3 offset:26112
	ds_read_b32 v148, v3 offset:26624
	ds_read_b32 v149, v3 offset:27136
	ds_read_b32 v150, v3 offset:27648
	ds_read_b32 v151, v3 offset:28160
	s_waitcnt lgkmcnt(0)
	ds_read_b32 v152, v3 offset:28672
	ds_read_b32 v153, v3 offset:29184
	ds_read_b32 v154, v3 offset:29696
	ds_read_b32 v155, v3 offset:30208
	ds_read_b32 v156, v3 offset:30720
	ds_read_b32 v157, v3 offset:31232
	ds_read_b32 v158, v3 offset:31744
	ds_read_b32 v159, v3 offset:32256
	s_waitcnt lgkmcnt(0)
; __device__ __forceinline__ unsigned f2bf(float f) { return pk2(f, 0.f) & 0xffffu; }
; __device__ __forceinline__ void hgrn_scan(const float* US, const float* DD, bf16* SB, int gtid, int gstride) {
;     ...
; #pragma unroll
;             for (int j = 0; j < 16; ++j) { SB[(size_t)(chain * 64 + c0 + j) * 16384 + idx] = (bf16)f2bf(run); run = d[j] * run + u[j]; } } }
	global_load_dword v56, v1, s[4:5]
	s_add_u32 s4, s4, 0x10000
	s_addc_u32 s5, s5, 0
	v_cvt_pk_bf16_f32 v5, v6, v169
	s_waitcnt vmcnt(24)
	global_store_short v2, v5, s[8:9]
	s_add_u32 s8, s8, 0x8000
	s_addc_u32 s9, s9, 0
	v_fmac_f32_e32 v32, v6, v96
	global_load_dword v57, v1, s[4:5]
	s_add_u32 s4, s4, 0x10000
	s_addc_u32 s5, s5, 0
	v_cvt_pk_bf16_f32 v5, v32, v169
	s_waitcnt vmcnt(25)
	global_store_short v2, v5, s[8:9]
	s_add_u32 s8, s8, 0x8000
	s_addc_u32 s9, s9, 0
	v_fmac_f32_e32 v33, v32, v97
	global_load_dword v58, v1, s[4:5]
	s_add_u32 s4, s4, 0x10000
	s_addc_u32 s5, s5, 0
	v_cvt_pk_bf16_f32 v5, v33, v169
	s_waitcnt vmcnt(26)
	global_store_short v2, v5, s[8:9]
	s_add_u32 s8, s8, 0x8000
	s_addc_u32 s9, s9, 0
	v_fmac_f32_e32 v34, v33, v98
	global_load_dword v59, v1, s[4:5]
	s_add_u32 s4, s4, 0x10000
	s_addc_u32 s5, s5, 0
	v_cvt_pk_bf16_f32 v5, v34, v169
	s_waitcnt vmcnt(27)
	global_store_short v2, v5, s[8:9]
	s_add_u32 s8, s8, 0x8000
	s_addc_u32 s9, s9, 0
	v_fmac_f32_e32 v35, v34, v99
	global_load_dword v60, v1, s[4:5]
	s_add_u32 s4, s4, 0x10000
	s_addc_u32 s5, s5, 0
	v_cvt_pk_bf16_f32 v5, v35, v169
	s_waitcnt vmcnt(28)
	global_store_short v2, v5, s[8:9]
	s_add_u32 s8, s8, 0x8000
	s_addc_u32 s9, s9, 0
	v_fmac_f32_e32 v36, v35, v100
	global_load_dword v61, v1, s[4:5]
	s_add_u32 s4, s4, 0x10000
	s_addc_u32 s5, s5, 0
	v_cvt_pk_bf16_f32 v5, v36, v169
	s_waitcnt vmcnt(29)
	global_store_short v2, v5, s[8:9]
	s_add_u32 s8, s8, 0x8000
	s_addc_u32 s9, s9, 0
	v_fmac_f32_e32 v37, v36, v101
	global_load_dword v62, v1, s[4:5]
	s_add_u32 s4, s4, 0x10000
	s_addc_u32 s5, s5, 0
	v_cvt_pk_bf16_f32 v5, v37, v169
	s_waitcnt vmcnt(30)
	global_store_short v2, v5, s[8:9]
	s_add_u32 s8, s8, 0x8000
	s_addc_u32 s9, s9, 0
	v_fmac_f32_e32 v38, v37, v102
	global_load_dword v63, v1, s[4:5]
	s_add_u32 s4, s4, 0x10000
	s_addc_u32 s5, s5, 0
	v_cvt_pk_bf16_f32 v5, v38, v169
	s_waitcnt vmcnt(31)
	global_store_short v2, v5, s[8:9]
	s_add_u32 s8, s8, 0x8000
	s_addc_u32 s9, s9, 0
	v_fmac_f32_e32 v39, v38, v103
	global_load_dword v64, v1, s[4:5]
	s_add_u32 s4, s4, 0x10000
	s_addc_u32 s5, s5, 0
	v_cvt_pk_bf16_f32 v5, v39, v169
	s_waitcnt vmcnt(32)
	global_store_short v2, v5, s[8:9]
	s_add_u32 s8, s8, 0x8000
	s_addc_u32 s9, s9, 0
	v_fmac_f32_e32 v40, v39, v104
	global_load_dword v65, v1, s[4:5]
	s_add_u32 s4, s4, 0x10000
	s_addc_u32 s5, s5, 0
	v_cvt_pk_bf16_f32 v5, v40, v169
	s_waitcnt vmcnt(33)
	global_store_short v2, v5, s[8:9]
	s_add_u32 s8, s8, 0x8000
	s_addc_u32 s9, s9, 0
	v_fmac_f32_e32 v41, v40, v105
	global_load_dword v66, v1, s[4:5]
	s_add_u32 s4, s4, 0x10000
	s_addc_u32 s5, s5, 0
	v_cvt_pk_bf16_f32 v5, v41, v169
	s_waitcnt vmcnt(34)
	global_store_short v2, v5, s[8:9]
	s_add_u32 s8, s8, 0x8000
	s_addc_u32 s9, s9, 0
	v_fmac_f32_e32 v42, v41, v106
	global_load_dword v67, v1, s[4:5]
	s_add_u32 s4, s4, 0x10000
	s_addc_u32 s5, s5, 0
	v_cvt_pk_bf16_f32 v5, v42, v169
	s_waitcnt vmcnt(35)
	global_store_short v2, v5, s[8:9]
	s_add_u32 s8, s8, 0x8000
	s_addc_u32 s9, s9, 0
	v_fmac_f32_e32 v43, v42, v107
	global_load_dword v68, v1, s[4:5]
	s_add_u32 s4, s4, 0x10000
	s_addc_u32 s5, s5, 0
	v_cvt_pk_bf16_f32 v5, v43, v169
	s_waitcnt vmcnt(36)
	global_store_short v2, v5, s[8:9]
	s_add_u32 s8, s8, 0x8000
	s_addc_u32 s9, s9, 0
	v_fmac_f32_e32 v44, v43, v108
	global_load_dword v69, v1, s[4:5]
	s_add_u32 s4, s4, 0x10000
	s_addc_u32 s5, s5, 0
	v_cvt_pk_bf16_f32 v5, v44, v169
	s_waitcnt vmcnt(37)
	global_store_short v2, v5, s[8:9]
	s_add_u32 s8, s8, 0x8000
	s_addc_u32 s9, s9, 0
	v_fmac_f32_e32 v45, v44, v109
	global_load_dword v70, v1, s[4:5]
	s_add_u32 s4, s4, 0x10000
	s_addc_u32 s5, s5, 0
	v_cvt_pk_bf16_f32 v5, v45, v169
	s_waitcnt vmcnt(38)
	global_store_short v2, v5, s[8:9]
	s_add_u32 s8, s8, 0x8000
	s_addc_u32 s9, s9, 0
	v_fmac_f32_e32 v46, v45, v110
	global_load_dword v71, v1, s[4:5]
	s_add_u32 s4, s4, 0x10000
	s_addc_u32 s5, s5, 0
	v_cvt_pk_bf16_f32 v5, v46, v169
	s_waitcnt vmcnt(39)
	global_store_short v2, v5, s[8:9]
	s_add_u32 s8, s8, 0x8000
	s_addc_u32 s9, s9, 0
	v_fmac_f32_e32 v47, v46, v111
	global_load_dword v72, v1, s[4:5]
	s_add_u32 s4, s4, 0x10000
	s_addc_u32 s5, s5, 0
	v_cvt_pk_bf16_f32 v5, v47, v169
	s_waitcnt vmcnt(40)
	global_store_short v2, v5, s[8:9]
	s_add_u32 s8, s8, 0x8000
	s_addc_u32 s9, s9, 0
	v_fmac_f32_e32 v48, v47, v112
	global_load_dword v73, v1, s[4:5]
	s_add_u32 s4, s4, 0x10000
	s_addc_u32 s5, s5, 0
	v_cvt_pk_bf16_f32 v5, v48, v169
	s_waitcnt vmcnt(41)
	global_store_short v2, v5, s[8:9]
	s_add_u32 s8, s8, 0x8000
	s_addc_u32 s9, s9, 0
	v_fmac_f32_e32 v49, v48, v113
	global_load_dword v74, v1, s[4:5]
	s_add_u32 s4, s4, 0x10000
	s_addc_u32 s5, s5, 0
	v_cvt_pk_bf16_f32 v5, v49, v169
	s_waitcnt vmcnt(42)
	global_store_short v2, v5, s[8:9]
	s_add_u32 s8, s8, 0x8000
	s_addc_u32 s9, s9, 0
	v_fmac_f32_e32 v50, v49, v114
	global_load_dword v75, v1, s[4:5]
	s_add_u32 s4, s4, 0x10000
	s_addc_u32 s5, s5, 0
	v_cvt_pk_bf16_f32 v5, v50, v169
	s_waitcnt vmcnt(43)
	global_store_short v2, v5, s[8:9]
	s_add_u32 s8, s8, 0x8000
	s_addc_u32 s9, s9, 0
	v_fmac_f32_e32 v51, v50, v115
	global_load_dword v76, v1, s[4:5]
	s_add_u32 s4, s4, 0x10000
	s_addc_u32 s5, s5, 0
	v_cvt_pk_bf16_f32 v5, v51, v169
	s_waitcnt vmcnt(44)
	global_store_short v2, v5, s[8:9]
	s_add_u32 s8, s8, 0x8000
	s_addc_u32 s9, s9, 0
	v_fmac_f32_e32 v52, v51, v116
	global_load_dword v77, v1, s[4:5]
	s_add_u32 s4, s4, 0x10000
	s_addc_u32 s5, s5, 0
	v_cvt_pk_bf16_f32 v5, v52, v169
	s_waitcnt vmcnt(45)
	global_store_short v2, v5, s[8:9]
	s_add_u32 s8, s8, 0x8000
	s_addc_u32 s9, s9, 0
	v_fmac_f32_e32 v53, v52, v117
	global_load_dword v78, v1, s[4:5]
	s_add_u32 s4, s4, 0x10000
	s_addc_u32 s5, s5, 0
	v_cvt_pk_bf16_f32 v5, v53, v169
	s_waitcnt vmcnt(46)
; __device__ __forceinline__ unsigned f2bf(float f) { return pk2(f, 0.f) & 0xffffu; }
; __device__ __forceinline__ void hgrn_scan(const float* US, const float* DD, bf16* SB, int gtid, int gstride) {
;     ...
; #pragma unroll
;             for (int j = 0; j < 16; ++j) { SB[(size_t)(chain * 64 + c0 + j) * 16384 + idx] = (bf16)f2bf(run); run = d[j] * run + u[j]; } } }
	global_store_short v2, v5, s[8:9]
	s_add_u32 s8, s8, 0x8000
	s_addc_u32 s9, s9, 0
	v_fmac_f32_e32 v54, v53, v118
	global_load_dword v79, v1, s[4:5]
	s_add_u32 s4, s4, 0x10000
	s_addc_u32 s5, s5, 0
	v_cvt_pk_bf16_f32 v5, v54, v169
	s_waitcnt vmcnt(47)
	global_store_short v2, v5, s[8:9]
	s_add_u32 s8, s8, 0x8000
	s_addc_u32 s9, s9, 0
	v_fmac_f32_e32 v55, v54, v119
	global_load_dword v80, v1, s[4:5]
	s_add_u32 s4, s4, 0x10000
	s_addc_u32 s5, s5, 0
	v_cvt_pk_bf16_f32 v5, v55, v169
	s_waitcnt vmcnt(48)
	global_store_short v2, v5, s[8:9]
	s_add_u32 s8, s8, 0x8000
	s_addc_u32 s9, s9, 0
	v_fmac_f32_e32 v56, v55, v120
	global_load_dword v81, v1, s[4:5]
	s_add_u32 s4, s4, 0x10000
	s_addc_u32 s5, s5, 0
	v_cvt_pk_bf16_f32 v5, v56, v169
	s_waitcnt vmcnt(48)
	global_store_short v2, v5, s[8:9]
	s_add_u32 s8, s8, 0x8000
	s_addc_u32 s9, s9, 0
	v_fmac_f32_e32 v57, v56, v121
	global_load_dword v82, v1, s[4:5]
	s_add_u32 s4, s4, 0x10000
	s_addc_u32 s5, s5, 0
	v_cvt_pk_bf16_f32 v5, v57, v169
	s_waitcnt vmcnt(48)
	global_store_short v2, v5, s[8:9]
	s_add_u32 s8, s8, 0x8000
	s_addc_u32 s9, s9, 0
	v_fmac_f32_e32 v58, v57, v122
	global_load_dword v83, v1, s[4:5]
	s_add_u32 s4, s4, 0x10000
	s_addc_u32 s5, s5, 0
	v_cvt_pk_bf16_f32 v5, v58, v169
	s_waitcnt vmcnt(48)
	global_store_short v2, v5, s[8:9]
	s_add_u32 s8, s8, 0x8000
	s_addc_u32 s9, s9, 0
	v_fmac_f32_e32 v59, v58, v123
	global_load_dword v84, v1, s[4:5]
	s_add_u32 s4, s4, 0x10000
	s_addc_u32 s5, s5, 0
	v_cvt_pk_bf16_f32 v5, v59, v169
	s_waitcnt vmcnt(48)
	global_store_short v2, v5, s[8:9]
	s_add_u32 s8, s8, 0x8000
	s_addc_u32 s9, s9, 0
	v_fmac_f32_e32 v60, v59, v124
	global_load_dword v85, v1, s[4:5]
	s_add_u32 s4, s4, 0x10000
	s_addc_u32 s5, s5, 0
	v_cvt_pk_bf16_f32 v5, v60, v169
	s_waitcnt vmcnt(48)
	global_store_short v2, v5, s[8:9]
	s_add_u32 s8, s8, 0x8000
	s_addc_u32 s9, s9, 0
	v_fmac_f32_e32 v61, v60, v125
	global_load_dword v86, v1, s[4:5]
	s_add_u32 s4, s4, 0x10000
	s_addc_u32 s5, s5, 0
	v_cvt_pk_bf16_f32 v5, v61, v169
	s_waitcnt vmcnt(48)
	global_store_short v2, v5, s[8:9]
	s_add_u32 s8, s8, 0x8000
	s_addc_u32 s9, s9, 0
	v_fmac_f32_e32 v62, v61, v126
	global_load_dword v87, v1, s[4:5]
	s_add_u32 s4, s4, 0x10000
	s_addc_u32 s5, s5, 0
	v_cvt_pk_bf16_f32 v5, v62, v169
	s_waitcnt vmcnt(48)
	global_store_short v2, v5, s[8:9]
	s_add_u32 s8, s8, 0x8000
	s_addc_u32 s9, s9, 0
	v_fmac_f32_e32 v63, v62, v127
	global_load_dword v88, v1, s[4:5]
	s_add_u32 s4, s4, 0x10000
	s_addc_u32 s5, s5, 0
	v_cvt_pk_bf16_f32 v5, v63, v169
	s_waitcnt vmcnt(48)
	global_store_short v2, v5, s[8:9]
	s_add_u32 s8, s8, 0x8000
	s_addc_u32 s9, s9, 0
	v_fmac_f32_e32 v64, v63, v128
	global_load_dword v89, v1, s[4:5]
	s_add_u32 s4, s4, 0x10000
	s_addc_u32 s5, s5, 0
	v_cvt_pk_bf16_f32 v5, v64, v169
	s_waitcnt vmcnt(48)
	global_store_short v2, v5, s[8:9]
	s_add_u32 s8, s8, 0x8000
	s_addc_u32 s9, s9, 0
	v_fmac_f32_e32 v65, v64, v129
	global_load_dword v90, v1, s[4:5]
	s_add_u32 s4, s4, 0x10000
	s_addc_u32 s5, s5, 0
	v_cvt_pk_bf16_f32 v5, v65, v169
	s_waitcnt vmcnt(48)
	global_store_short v2, v5, s[8:9]
	s_add_u32 s8, s8, 0x8000
	s_addc_u32 s9, s9, 0
	v_fmac_f32_e32 v66, v65, v130
	global_load_dword v91, v1, s[4:5]
	s_add_u32 s4, s4, 0x10000
	s_addc_u32 s5, s5, 0
	v_cvt_pk_bf16_f32 v5, v66, v169
	s_waitcnt vmcnt(48)
	global_store_short v2, v5, s[8:9]
	s_add_u32 s8, s8, 0x8000
	s_addc_u32 s9, s9, 0
	v_fmac_f32_e32 v67, v66, v131
	global_load_dword v92, v1, s[4:5]
	s_add_u32 s4, s4, 0x10000
	s_addc_u32 s5, s5, 0
	v_cvt_pk_bf16_f32 v5, v67, v169
	s_waitcnt vmcnt(48)
	global_store_short v2, v5, s[8:9]
	s_add_u32 s8, s8, 0x8000
	s_addc_u32 s9, s9, 0
	v_fmac_f32_e32 v68, v67, v132
	global_load_dword v93, v1, s[4:5]
	s_add_u32 s4, s4, 0x10000
	s_addc_u32 s5, s5, 0
	v_cvt_pk_bf16_f32 v5, v68, v169
	s_waitcnt vmcnt(48)
	global_store_short v2, v5, s[8:9]
	s_add_u32 s8, s8, 0x8000
	s_addc_u32 s9, s9, 0
	v_fmac_f32_e32 v69, v68, v133
	global_load_dword v94, v1, s[4:5]
	s_add_u32 s4, s4, 0x10000
	s_addc_u32 s5, s5, 0
	v_cvt_pk_bf16_f32 v5, v69, v169
	s_waitcnt vmcnt(48)
	global_store_short v2, v5, s[8:9]
	s_add_u32 s8, s8, 0x8000
	s_addc_u32 s9, s9, 0
	v_fmac_f32_e32 v70, v69, v134
	global_load_dword v95, v1, s[4:5]
	v_cvt_pk_bf16_f32 v5, v70, v169
	s_waitcnt vmcnt(48)
	global_store_short v2, v5, s[8:9]
	s_add_u32 s8, s8, 0x8000
	s_addc_u32 s9, s9, 0
	v_fmac_f32_e32 v71, v70, v135
	v_cvt_pk_bf16_f32 v5, v71, v169
	s_waitcnt vmcnt(47)
; __device__ __forceinline__ unsigned f2bf(float f) { return pk2(f, 0.f) & 0xffffu; }
; __device__ __forceinline__ void hgrn_scan(const float* US, const float* DD, bf16* SB, int gtid, int gstride) {
;     for (int e = gtid; e < 8 * 16384; e += gstride) { const int chain = e >> 14, idx = e & 16383, k = idx & 127; float run = 0.f;
;         for (int c0 = 0; c0 < 64; c0 += 16) { float u[16], d[16];
; #pragma unroll
;             for (int j = 0; j < 16; ++j) { u[j] = US[(size_t)(chain * 64 + c0 + j) * 16384 + idx]; d[j] = DD[(chain * 64 + c0 + j) * 128 + k]; }
; #pragma unroll
;             for (int j = 0; j < 16; ++j) { SB[(size_t)(chain * 64 + c0 + j) * 16384 + idx] = (bf16)f2bf(run); run = d[j] * run + u[j]; } } }
; }
	global_store_short v2, v5, s[8:9]
	s_add_u32 s8, s8, 0x8000
	s_addc_u32 s9, s9, 0
	v_fmac_f32_e32 v72, v71, v136
	v_cvt_pk_bf16_f32 v5, v72, v169
	s_waitcnt vmcnt(46)
	global_store_short v2, v5, s[8:9]
	s_add_u32 s8, s8, 0x8000
	s_addc_u32 s9, s9, 0
	v_fmac_f32_e32 v73, v72, v137
	v_cvt_pk_bf16_f32 v5, v73, v169
	s_waitcnt vmcnt(45)
	global_store_short v2, v5, s[8:9]
	s_add_u32 s8, s8, 0x8000
	s_addc_u32 s9, s9, 0
	v_fmac_f32_e32 v74, v73, v138
	v_cvt_pk_bf16_f32 v5, v74, v169
	s_waitcnt vmcnt(44)
	global_store_short v2, v5, s[8:9]
	s_add_u32 s8, s8, 0x8000
	s_addc_u32 s9, s9, 0
	v_fmac_f32_e32 v75, v74, v139
	v_cvt_pk_bf16_f32 v5, v75, v169
	s_waitcnt vmcnt(43)
	global_store_short v2, v5, s[8:9]
	s_add_u32 s8, s8, 0x8000
	s_addc_u32 s9, s9, 0
	v_fmac_f32_e32 v76, v75, v140
	v_cvt_pk_bf16_f32 v5, v76, v169
	s_waitcnt vmcnt(42)
	global_store_short v2, v5, s[8:9]
	s_add_u32 s8, s8, 0x8000
	s_addc_u32 s9, s9, 0
	v_fmac_f32_e32 v77, v76, v141
	v_cvt_pk_bf16_f32 v5, v77, v169
	s_waitcnt vmcnt(41)
	global_store_short v2, v5, s[8:9]
	s_add_u32 s8, s8, 0x8000
	s_addc_u32 s9, s9, 0
	v_fmac_f32_e32 v78, v77, v142
	v_cvt_pk_bf16_f32 v5, v78, v169
	s_waitcnt vmcnt(40)
	global_store_short v2, v5, s[8:9]
	s_add_u32 s8, s8, 0x8000
	s_addc_u32 s9, s9, 0
	v_fmac_f32_e32 v79, v78, v143
	v_cvt_pk_bf16_f32 v5, v79, v169
	s_waitcnt vmcnt(39)
	global_store_short v2, v5, s[8:9]
	s_add_u32 s8, s8, 0x8000
	s_addc_u32 s9, s9, 0
	v_fmac_f32_e32 v80, v79, v144
	v_cvt_pk_bf16_f32 v5, v80, v169
	s_waitcnt vmcnt(38)
	global_store_short v2, v5, s[8:9]
	s_add_u32 s8, s8, 0x8000
	s_addc_u32 s9, s9, 0
	v_fmac_f32_e32 v81, v80, v145
	v_cvt_pk_bf16_f32 v5, v81, v169
	s_waitcnt vmcnt(37)
	global_store_short v2, v5, s[8:9]
	s_add_u32 s8, s8, 0x8000
	s_addc_u32 s9, s9, 0
	v_fmac_f32_e32 v82, v81, v146
	v_cvt_pk_bf16_f32 v5, v82, v169
	s_waitcnt vmcnt(36)
	global_store_short v2, v5, s[8:9]
	s_add_u32 s8, s8, 0x8000
	s_addc_u32 s9, s9, 0
	v_fmac_f32_e32 v83, v82, v147
	v_cvt_pk_bf16_f32 v5, v83, v169
	s_waitcnt vmcnt(35)
	global_store_short v2, v5, s[8:9]
	s_add_u32 s8, s8, 0x8000
	s_addc_u32 s9, s9, 0
	v_fmac_f32_e32 v84, v83, v148
	v_cvt_pk_bf16_f32 v5, v84, v169
	s_waitcnt vmcnt(34)
	global_store_short v2, v5, s[8:9]
	s_add_u32 s8, s8, 0x8000
	s_addc_u32 s9, s9, 0
	v_fmac_f32_e32 v85, v84, v149
	v_cvt_pk_bf16_f32 v5, v85, v169
	s_waitcnt vmcnt(33)
	global_store_short v2, v5, s[8:9]
	s_add_u32 s8, s8, 0x8000
	s_addc_u32 s9, s9, 0
	v_fmac_f32_e32 v86, v85, v150
	v_cvt_pk_bf16_f32 v5, v86, v169
	s_waitcnt vmcnt(32)
	global_store_short v2, v5, s[8:9]
	s_add_u32 s8, s8, 0x8000
	s_addc_u32 s9, s9, 0
	v_fmac_f32_e32 v87, v86, v151
	v_cvt_pk_bf16_f32 v5, v87, v169
	s_waitcnt vmcnt(31)
	global_store_short v2, v5, s[8:9]
	s_add_u32 s8, s8, 0x8000
	s_addc_u32 s9, s9, 0
	v_fmac_f32_e32 v88, v87, v152
	v_cvt_pk_bf16_f32 v5, v88, v169
	s_waitcnt vmcnt(30)
	global_store_short v2, v5, s[8:9]
	s_add_u32 s8, s8, 0x8000
	s_addc_u32 s9, s9, 0
	v_fmac_f32_e32 v89, v88, v153
	v_cvt_pk_bf16_f32 v5, v89, v169
	s_waitcnt vmcnt(29)
	global_store_short v2, v5, s[8:9]
	s_add_u32 s8, s8, 0x8000
	s_addc_u32 s9, s9, 0
	v_fmac_f32_e32 v90, v89, v154
	v_cvt_pk_bf16_f32 v5, v90, v169
	s_waitcnt vmcnt(28)
	global_store_short v2, v5, s[8:9]
	s_add_u32 s8, s8, 0x8000
	s_addc_u32 s9, s9, 0
	v_fmac_f32_e32 v91, v90, v155
	v_cvt_pk_bf16_f32 v5, v91, v169
	s_waitcnt vmcnt(27)
	global_store_short v2, v5, s[8:9]
	s_add_u32 s8, s8, 0x8000
	s_addc_u32 s9, s9, 0
	v_fmac_f32_e32 v92, v91, v156
	v_cvt_pk_bf16_f32 v5, v92, v169
	s_waitcnt vmcnt(26)
	global_store_short v2, v5, s[8:9]
	s_add_u32 s8, s8, 0x8000
	s_addc_u32 s9, s9, 0
	v_fmac_f32_e32 v93, v92, v157
	v_cvt_pk_bf16_f32 v5, v93, v169
	s_waitcnt vmcnt(25)
	global_store_short v2, v5, s[8:9]
	s_add_u32 s8, s8, 0x8000
	s_addc_u32 s9, s9, 0
	v_fmac_f32_e32 v94, v93, v158
	v_cvt_pk_bf16_f32 v5, v94, v169
	s_waitcnt vmcnt(24)
	global_store_short v2, v5, s[8:9]
	s_mov_b64 s[2:3], exec
	s_branch .LBB0_646
.Lscan_orig:
	s_mov_b32 s2, 0x20000
	v_add_u32_e32 v8, s0, v0
	s_mov_b64 s[0:1], s[20:21]
	v_cmp_gt_i32_e32 vcc, s2, v8
	s_and_saveexec_b64 s[2:3], vcc
	s_cbranch_execz .LBB0_646
	s_add_u32 s4, s0, 0x1d800000
	v_and_b32_e32 v1, 0x7f, v0
	v_readlane_b32 s8, v254, 38
	s_addc_u32 s5, s1, 0
	v_or_b32_e32 v9, 0x780, v1
	v_add_u16_e32 v10, s8, v0
	s_mov_b64 s[8:9], 0
